# SWA attention: all K/V tiles of an item staged by LDS-DMA at item start into a resident LDS image (no per-tile load-wait-write-barrier chain), counted vmcnt per tile pair
# speedup vs baseline: 1.0314x; 1.0048x over previous
.LBB0_274:
	s_or_b64 exec, exec, s[4:5]
	s_cmpk_lt_i32 s2, 0x400
	s_cselect_b64 s[0:1], -1, 0
	v_writelane_b32 v246, s0, 40
	s_cmpk_lt_i32 s2, 0x100
	s_mul_i32 s31, s31, s30
	v_writelane_b32 v246, s1, 41
	s_cselect_b64 s[0:1], -1, 0
	v_writelane_b32 v246, s0, 42
	s_mul_i32 s31, s31, s3
	s_movk_i32 s78, 0x400
	v_writelane_b32 v246, s1, 43
	s_movk_i32 s28, 0x600
	v_readlane_b32 s4, v246, 0
	v_readlane_b32 s16, v246, 12
	v_readlane_b32 s17, v246, 13
	s_cmp_lg_u64 s[16:17], 0
	s_cselect_b64 s[34:35], -1, 0
	s_cmpk_lt_i32 s2, 0xc0
	s_cselect_b64 s[0:1], -1, 0
	s_lshl_b32 s71, s30, 3
	v_readlane_b32 s5, v246, 1
	v_readlane_b32 s6, v246, 2
	v_readlane_b32 s7, v246, 3
	v_readlane_b32 s8, v246, 4
	v_readlane_b32 s9, v246, 5
	v_readlane_b32 s10, v246, 6
	v_readlane_b32 s11, v246, 7
	v_readlane_b32 s12, v246, 8
	v_readlane_b32 s13, v246, 9
	v_readlane_b32 s14, v246, 10
	v_readlane_b32 s15, v246, 11
	v_readlane_b32 s18, v246, 14
	v_readlane_b32 s19, v246, 15
	v_writelane_b32 v246, s0, 44
	s_cmpk_lt_i32 s2, 0x380
	s_mov_b32 s29, 0x2aaaaaab
	v_writelane_b32 v246, s1, 45
	s_cselect_b64 s[0:1], -1, 0
	s_abs_i32 s4, s30
	s_waitcnt lgkmcnt(0)
	v_cvt_f32_u32_e32 v0, s4
	s_sub_i32 s5, 0, s4
	s_add_i32 s3, s30, 0x1ff
	v_writelane_b32 v246, s0, 46
	v_rcp_iflag_f32_e32 v0, v0
	s_mov_b32 s46, 0x3ffff0
	v_writelane_b32 v246, s1, 47
	s_movk_i32 s0, 0x180
	v_mul_f32_e32 v0, 0x4f7ffffe, v0
	v_cvt_u32_f32_e32 v0, v0
	v_mov_b32_e32 v1, 0
	s_mov_b32 s36, 0x10000
	s_movk_i32 s38, 0xc000
	v_readfirstlane_b32 s6, v0
	s_mul_i32 s5, s5, s6
	s_mul_hi_u32 s5, s6, s5
	s_add_i32 s6, s6, s5
	s_mul_hi_u32 s5, s6, 0x180
	s_mul_i32 s5, s5, s4
	s_sub_i32 s5, 0x180, s5
	s_sub_i32 s7, s5, s4
	s_cmp_ge_u32 s5, s4
	s_cselect_b32 s5, s7, s5
	s_sub_i32 s7, s5, s4
	s_cmp_ge_u32 s5, s4
	s_cselect_b32 s5, s7, s5
	s_sub_i32 s1, 0x180, s5
	s_cmp_lt_i32 s2, s1
	s_cselect_b64 s[8:9], -1, 0
	s_lshl_b32 s68, s5, 1
	v_writelane_b32 v246, s8, 48
	s_cmp_lt_i32 s2, s68
	s_mov_b32 s41, 0xc2fc0000
	v_writelane_b32 v246, s9, 49
	s_cselect_b64 s[8:9], -1, 0
	s_sub_i32 s7, 0xfffffe01, s30
	s_xor_b32 s5, s3, s30
	s_max_i32 s3, s3, s7
	v_writelane_b32 v246, s8, 50
	s_mul_hi_u32 s7, s3, s6
	s_ashr_i32 s5, s5, 31
	v_writelane_b32 v246, s9, 51
	s_mul_i32 s8, s7, s4
	s_sub_i32 s3, s3, s8
	s_add_i32 s8, s7, 1
	s_sub_i32 s9, s3, s4
	s_cmp_ge_u32 s3, s4
	s_cselect_b32 s7, s8, s7
	s_cselect_b32 s3, s9, s3
	s_add_i32 s8, s7, 1
	s_cmp_ge_u32 s3, s4
	s_cselect_b32 s3, s8, s7
	s_xor_b32 s3, s3, s5
	s_sub_i32 s69, s3, s5
	s_mul_hi_u32 s3, s6, 0x580
	s_cmp_gt_i32 s69, 0
	s_mul_i32 s3, s3, s4
	s_cselect_b64 s[8:9], -1, 0
	s_sub_i32 s3, 0x580, s3
	s_sub_i32 s5, s3, s4
	s_cmp_ge_u32 s3, s4
	s_cselect_b32 s3, s5, s3
	s_sub_i32 s5, s3, s4
	s_cmp_ge_u32 s3, s4
	s_cselect_b32 s3, s5, s3
	s_sub_i32 s33, 0x580, s3
	v_writelane_b32 v246, s8, 52
	s_cmp_lt_i32 s2, s33
	s_cselect_b64 s[4:5], -1, 0
	v_writelane_b32 v246, s9, 53
	s_lshl_b32 s47, s3, 1
	v_writelane_b32 v246, s4, 54
	s_cmp_lt_i32 s2, s47
	s_mov_b32 s3, 0x18000
	v_writelane_b32 v246, s5, 55
	s_cselect_b64 s[4:5], -1, 0
	v_writelane_b32 v246, s4, 56
	s_add_i32 s39, s3, 0x400
	s_movk_i32 s3, 0x5000
	v_writelane_b32 v246, s5, 57
	s_addk_i32 s3, 0x400
	v_writelane_b32 v246, s3, 58
	s_mov_b32 s3, 0xd000
	s_addk_i32 s3, 0x400
	s_movk_i32 s37, 0x80
	v_mov_b32_e32 v163, 0x3000
	v_mov_b32_e32 v165, 1
	s_movk_i32 s49, 0x90
	s_mov_b32 s42, 0x800000
	s_movk_i32 s43, 0x3fff
	s_movk_i32 s44, 0x300
	s_movk_i32 s45, 0xc00
	s_movk_i32 s48, 0x1a0
	v_writelane_b32 v246, s3, 59
	v_mov_b32_e32 v178, 0x3727c5ac
	s_movk_i32 s79, 0x1600
	v_mov_b32_e32 v179, 0x400
	v_mov_b32_e32 v180, 0x3e38aa3b
	v_mov_b32_e32 v181, 0x42800000
	v_not_b32_e32 v182, 63
	v_mov_b32_e32 v183, 0x1200
	v_mov_b32_e32 v184, 0xff800000
	v_mov_b32_e32 v164, 0x358637bd
	v_bfrev_b32_e32 v185, 0.5
	s_mov_b32 s3, 0
	s_mov_b32 s55, 0
	s_mov_b32 s70, 0x3fd744fd
	s_barrier
	s_branch .LBB0_278

.LBB0_381:
	s_ashr_i32 s4, s87, 4
	s_lshl_b32 s9, s4, 8
	s_and_b32 s88, s87, 15
	s_add_i32 s5, s9, 0xffffff80
	s_cmp_gt_i32 s4, 0
	s_cselect_b32 s8, s5, 0
	s_lshl_b32 s4, s88, 7
	s_add_u32 s58, s60, s4
	s_addc_u32 s59, s61, 0
	s_lshl_b32 s4, s87, 19
	s_and_b32 s10, s4, 0x600000
	s_add_u32 s4, s72, s10
	s_addc_u32 s5, s73, 0
	s_add_u32 s10, s74, s10
	v_readlane_b32 s12, v246, 0
	s_addc_u32 s11, s75, 0
	s_or_b32 s54, s88, s86
	v_readlane_b32 s16, v246, 4
	v_readlane_b32 s17, v246, 5
	v_readlane_b32 s20, v246, 8
	v_readlane_b32 s21, v246, 9
	s_lshl_b64 s[80:81], s[54:55], 2
	s_mov_b64 s[16:17], s[20:21]
	s_add_u32 s80, s16, s80
	s_addc_u32 s81, s17, s81
	v_mov_b32_e32 v6, v162
	global_load_dword v14, v1, s[80:81]
	s_sub_i32 s80, s9, s8
	v_ashrrev_i32_e32 v0, 1, v6
	v_and_b32_e32 v0, 0xffffffe0, v0
	v_and_b32_e32 v13, 31, v6
	v_add_u32_e32 v93, s9, v0
	v_or_b32_e32 v86, v93, v13
	v_ashrrev_i32_e32 v87, 31, v86
	v_lshlrev_b64 v[82:83], 11, v[86:87]
	s_mov_b32 s9, s55
	v_bfe_u32 v12, v6, 5, 1
	v_lshl_add_u64 v[2:3], s[58:59], 0, v[82:83]
	v_and_b32_e32 v120, 15, v6
	v_bfe_u32 v121, v6, 4, 2
	v_add_u32_e32 v122, v93, v120
	v_ashrrev_i32_e32 v123, 31, v122
	v_lshlrev_b64 v[116:117], 11, v[122:123]
	v_lshl_add_u64 v[116:117], s[58:59], 0, v[116:117]
	v_lshlrev_b32_e32 v120, 4, v121
	v_mov_b32_e32 v121, 0
	v_lshl_add_u64 v[116:117], v[116:117], 0, v[120:121]
	v_add_co_u32_e32 v118, vcc, 0x8000, v116
	s_nop 1
	v_addc_co_u32_e32 v119, vcc, 0, v117, vcc
	s_addk_i32 s80, 0x100
	s_lshl_b64 s[58:59], s[8:9], 7
	v_lshlrev_b32_e32 v0, 4, v12
	s_add_u32 s58, s4, s58
	v_ashrrev_i32_e32 v7, 31, v6
	v_lshl_add_u64 v[16:17], v[2:3], 0, v[0:1]
	s_addc_u32 s59, s5, s59
	v_lshlrev_b64 v[2:3], 4, v[6:7]
	v_lshl_add_u64 v[4:5], s[58:59], 0, v[2:3]
	global_load_dwordx4 v[50:53], v[116:117], off
	global_load_dwordx4 v[54:57], v[116:117], off offset:64
	global_load_dwordx4 v[58:61], v[118:119], off
	v_lshrrev_b32_e32 v4, 29, v7
	v_add_u32_e32 v7, v6, v4
	s_lshl_b64 s[58:59], s[8:9], 1
	v_ashrrev_i32_e32 v18, 3, v7
	v_and_b32_e32 v7, -8, v7
	s_add_u32 s58, s10, s58
	v_ashrrev_i32_e32 v19, 31, v18
	v_sub_u32_e32 v7, v6, v7
	s_addc_u32 s59, s11, s59
	v_lshlrev_b64 v[4:5], 15, v[18:19]
	v_lshlrev_b32_e32 v8, 3, v7
	v_lshl_add_u64 v[10:11], s[58:59], 0, v[4:5]
	v_ashrrev_i32_e32 v9, 31, v8
	v_lshl_add_u64 v[10:11], v[8:9], 1, v[10:11]
	global_load_dwordx4 v[66:69], v[118:119], off offset:64
	v_readlane_b32 s13, v246, 1
	v_readlane_b32 s14, v246, 2
	v_readlane_b32 s15, v246, 3
	v_readlane_b32 s18, v246, 6
	v_readlane_b32 s19, v246, 7
	v_readlane_b32 s22, v246, 10
	v_readlane_b32 s23, v246, 11
	v_readlane_b32 s24, v246, 12
	v_readlane_b32 s25, v246, 13
	v_readlane_b32 s26, v246, 14
	v_readlane_b32 s27, v246, 15
	v_readfirstlane_b32 s12, v162
	s_lshl_b32 s14, s8, 7
	s_lshr_b32 s12, s12, 6
	s_add_u32 s14, s4, s14
	s_addc_u32 s15, s5, 0
	s_lshl_b32 s16, s8, 1
	s_add_u32 s16, s10, s16
	s_addc_u32 s17, s11, 0
	s_add_i32 s18, s12, 0
	s_mul_i32 s19, s18, 205
	s_lshr_b32 s19, s19, 11
	s_mul_i32 s20, s19, 10
	s_sub_i32 s20, s18, s20
	v_and_b32_e32 v191, 63, v162
	v_lshl_add_u32 v191, s20, 6, v191
	v_mul_u32_u24_e32 v192, 0xcd, v191
	v_lshrrev_b32_e32 v192, 11, v192
	v_mul_u32_u24_e32 v193, 10, v192
	v_sub_u32_e32 v191, v191, v193
	v_min_u32_e32 v191, 7, v191
	s_movk_i32 s21, 0x80
	s_movk_i32 s22, 0x2000
	s_bitcmp1_b32 s19, 1
	s_cselect_b32 s21, 0x8000, s21
	s_cselect_b32 s22, 0x80, s22
	s_bitcmp1_b32 s19, 0
	s_cselect_b32 s22, s22, 0
	v_mul_u32_u24_e32 v192, s21, v192
	v_lshl_add_u32 v192, v191, 4, v192
	v_add_u32_e32 v186, s22, v192
	s_add_i32 s18, s12, 8
	s_mul_i32 s19, s18, 205
	s_lshr_b32 s19, s19, 11
	s_mul_i32 s20, s19, 10
	s_sub_i32 s20, s18, s20
	v_and_b32_e32 v191, 63, v162
	v_lshl_add_u32 v191, s20, 6, v191
	v_mul_u32_u24_e32 v192, 0xcd, v191
	v_lshrrev_b32_e32 v192, 11, v192
	v_mul_u32_u24_e32 v193, 10, v192
	v_sub_u32_e32 v191, v191, v193
	v_min_u32_e32 v191, 7, v191
	s_movk_i32 s21, 0x80
	s_movk_i32 s22, 0x2000
	s_bitcmp1_b32 s19, 1
	s_cselect_b32 s21, 0x8000, s21
	s_cselect_b32 s22, 0x80, s22
	s_bitcmp1_b32 s19, 0
	s_cselect_b32 s22, s22, 0
	v_mul_u32_u24_e32 v192, s21, v192
	v_lshl_add_u32 v192, v191, 4, v192
	v_add_u32_e32 v187, s22, v192
	s_add_i32 s18, s12, 16
	s_mul_i32 s19, s18, 205
	s_lshr_b32 s19, s19, 11
	s_mul_i32 s20, s19, 10
	s_sub_i32 s20, s18, s20
	v_and_b32_e32 v191, 63, v162
	v_lshl_add_u32 v191, s20, 6, v191
	v_mul_u32_u24_e32 v192, 0xcd, v191
	v_lshrrev_b32_e32 v192, 11, v192
	v_mul_u32_u24_e32 v193, 10, v192
	v_sub_u32_e32 v191, v191, v193
	v_min_u32_e32 v191, 7, v191
	s_movk_i32 s21, 0x80
	s_movk_i32 s22, 0x2000
	s_bitcmp1_b32 s19, 1
	s_cselect_b32 s21, 0x8000, s21
	s_cselect_b32 s22, 0x80, s22
	s_bitcmp1_b32 s19, 0
	s_cselect_b32 s22, s22, 0
	v_mul_u32_u24_e32 v192, s21, v192
	v_lshl_add_u32 v192, v191, 4, v192
	v_add_u32_e32 v188, s22, v192
	s_add_i32 s18, s12, 24
	s_mul_i32 s19, s18, 205
	s_lshr_b32 s19, s19, 11
	s_mul_i32 s20, s19, 10
	s_sub_i32 s20, s18, s20
	v_and_b32_e32 v191, 63, v162
	v_lshl_add_u32 v191, s20, 6, v191
	v_mul_u32_u24_e32 v192, 0xcd, v191
	v_lshrrev_b32_e32 v192, 11, v192
	v_mul_u32_u24_e32 v193, 10, v192
	v_sub_u32_e32 v191, v191, v193
	v_min_u32_e32 v191, 7, v191
	s_movk_i32 s21, 0x80
	s_movk_i32 s22, 0x2000
	s_bitcmp1_b32 s19, 1
	s_cselect_b32 s21, 0x8000, s21
	s_cselect_b32 s22, 0x80, s22
	s_bitcmp1_b32 s19, 0
	s_cselect_b32 s22, s22, 0
	v_mul_u32_u24_e32 v192, s21, v192
	v_lshl_add_u32 v192, v191, 4, v192
	v_add_u32_e32 v189, s22, v192
	s_add_i32 s18, s12, 32
	s_mul_i32 s19, s18, 205
	s_lshr_b32 s19, s19, 11
	s_mul_i32 s20, s19, 10
	s_sub_i32 s20, s18, s20
	v_and_b32_e32 v191, 63, v162
	v_lshl_add_u32 v191, s20, 6, v191
	v_mul_u32_u24_e32 v192, 0xcd, v191
	v_lshrrev_b32_e32 v192, 11, v192
	v_mul_u32_u24_e32 v193, 10, v192
	v_sub_u32_e32 v191, v191, v193
	v_min_u32_e32 v191, 7, v191
	s_movk_i32 s21, 0x80
	s_movk_i32 s22, 0x2000
	s_bitcmp1_b32 s19, 1
	s_cselect_b32 s21, 0x8000, s21
	s_cselect_b32 s22, 0x80, s22
	s_bitcmp1_b32 s19, 0
	s_cselect_b32 s22, s22, 0
	v_mul_u32_u24_e32 v192, s21, v192
	v_lshl_add_u32 v192, v191, 4, v192
	v_add_u32_e32 v190, s22, v192
	s_add_i32 s18, s12, 0
	s_mul_i32 s19, s18, 205
	s_lshr_b32 s19, s19, 11
	s_lshl_b32 s24, s18, 10
	s_add_u32 m0, s24, 0x400
	s_mov_b32 s25, 0x0
	s_bitcmp1_b32 s19, 1
	s_cselect_b32 s26, s16, s14
	s_cselect_b32 s27, s17, s15
	s_cselect_b32 s25, 0x0, s25
	s_add_u32 s26, s26, s25
	s_addc_u32 s27, s27, 0
	global_load_lds_dwordx4 v186, s[26:27]
	s_add_i32 s18, s12, 8
	s_mul_i32 s19, s18, 205
	s_lshr_b32 s19, s19, 11
	s_lshl_b32 s24, s18, 10
	s_add_u32 m0, s24, 0x400
	s_mov_b32 s25, 0x0
	s_bitcmp1_b32 s19, 1
	s_cselect_b32 s26, s16, s14
	s_cselect_b32 s27, s17, s15
	s_cselect_b32 s25, 0x0, s25
	s_add_u32 s26, s26, s25
	s_addc_u32 s27, s27, 0
	global_load_lds_dwordx4 v187, s[26:27]
	s_add_i32 s18, s12, 16
	s_mul_i32 s19, s18, 205
	s_lshr_b32 s19, s19, 11
	s_lshl_b32 s24, s18, 10
	s_add_u32 m0, s24, 0x400
	s_mov_b32 s25, 0x0
	s_bitcmp1_b32 s19, 1
	s_cselect_b32 s26, s16, s14
	s_cselect_b32 s27, s17, s15
	s_cselect_b32 s25, 0x0, s25
	s_add_u32 s26, s26, s25
	s_addc_u32 s27, s27, 0
	global_load_lds_dwordx4 v188, s[26:27]
	s_add_i32 s18, s12, 24
	s_mul_i32 s19, s18, 205
	s_lshr_b32 s19, s19, 11
	s_lshl_b32 s24, s18, 10
	s_add_u32 m0, s24, 0x400
	s_mov_b32 s25, 0x0
	s_bitcmp1_b32 s19, 1
	s_cselect_b32 s26, s16, s14
	s_cselect_b32 s27, s17, s15
	s_cselect_b32 s25, 0x0, s25
	s_add_u32 s26, s26, s25
	s_addc_u32 s27, s27, 0
	global_load_lds_dwordx4 v189, s[26:27]
	s_add_i32 s18, s12, 32
	s_mul_i32 s19, s18, 205
	s_lshr_b32 s19, s19, 11
	s_lshl_b32 s24, s18, 10
	s_add_u32 m0, s24, 0x400
	s_mov_b32 s25, 0x0
	s_bitcmp1_b32 s19, 1
	s_cselect_b32 s26, s16, s14
	s_cselect_b32 s27, s17, s15
	s_cselect_b32 s25, 0x0, s25
	s_add_u32 s26, s26, s25
	s_addc_u32 s27, s27, 0
	global_load_lds_dwordx4 v190, s[26:27]
	s_add_i32 s18, s12, 0
	s_mul_i32 s19, s18, 205
	s_lshr_b32 s19, s19, 11
	s_lshl_b32 s24, s18, 10
	s_add_u32 m0, s24, 0xa400
	s_mov_b32 s25, 0x4000
	s_bitcmp1_b32 s19, 1
	s_cselect_b32 s26, s16, s14
	s_cselect_b32 s27, s17, s15
	s_cselect_b32 s25, 0x100, s25
	s_add_u32 s26, s26, s25
	s_addc_u32 s27, s27, 0
	global_load_lds_dwordx4 v186, s[26:27]
	s_add_i32 s18, s12, 8
	s_mul_i32 s19, s18, 205
	s_lshr_b32 s19, s19, 11
	s_lshl_b32 s24, s18, 10
	s_add_u32 m0, s24, 0xa400
	s_mov_b32 s25, 0x4000
	s_bitcmp1_b32 s19, 1
	s_cselect_b32 s26, s16, s14
	s_cselect_b32 s27, s17, s15
	s_cselect_b32 s25, 0x100, s25
	s_add_u32 s26, s26, s25
	s_addc_u32 s27, s27, 0
	global_load_lds_dwordx4 v187, s[26:27]
	s_add_i32 s18, s12, 16
	s_mul_i32 s19, s18, 205
	s_lshr_b32 s19, s19, 11
	s_lshl_b32 s24, s18, 10
	s_add_u32 m0, s24, 0xa400
	s_mov_b32 s25, 0x4000
	s_bitcmp1_b32 s19, 1
	s_cselect_b32 s26, s16, s14
	s_cselect_b32 s27, s17, s15
	s_cselect_b32 s25, 0x100, s25
	s_add_u32 s26, s26, s25
	s_addc_u32 s27, s27, 0
	global_load_lds_dwordx4 v188, s[26:27]
	s_add_i32 s18, s12, 24
	s_mul_i32 s19, s18, 205
	s_lshr_b32 s19, s19, 11
	s_lshl_b32 s24, s18, 10
	s_add_u32 m0, s24, 0xa400
	s_mov_b32 s25, 0x4000
	s_bitcmp1_b32 s19, 1
	s_cselect_b32 s26, s16, s14
	s_cselect_b32 s27, s17, s15
	s_cselect_b32 s25, 0x100, s25
	s_add_u32 s26, s26, s25
	s_addc_u32 s27, s27, 0
	global_load_lds_dwordx4 v189, s[26:27]
	s_add_i32 s18, s12, 32
	s_mul_i32 s19, s18, 205
	s_lshr_b32 s19, s19, 11
	s_lshl_b32 s24, s18, 10
	s_add_u32 m0, s24, 0xa400
	s_mov_b32 s25, 0x4000
	s_bitcmp1_b32 s19, 1
	s_cselect_b32 s26, s16, s14
	s_cselect_b32 s27, s17, s15
	s_cselect_b32 s25, 0x100, s25
	s_add_u32 s26, s26, s25
	s_addc_u32 s27, s27, 0
	global_load_lds_dwordx4 v190, s[26:27]
	s_cmpk_lt_i32 s80, 0x180
	s_cbranch_scc1 .Lw3_dma_2pairs
	s_add_i32 s18, s12, 0
	s_mul_i32 s19, s18, 205
	s_lshr_b32 s19, s19, 11
	s_lshl_b32 s24, s18, 10
	s_add_u32 m0, s24, 0x14400
	s_mov_b32 s25, 0x8000
	s_bitcmp1_b32 s19, 1
	s_cselect_b32 s26, s16, s14
	s_cselect_b32 s27, s17, s15
	s_cselect_b32 s25, 0x200, s25
	s_add_u32 s26, s26, s25
	s_addc_u32 s27, s27, 0
	global_load_lds_dwordx4 v186, s[26:27]
	s_add_i32 s18, s12, 8
	s_mul_i32 s19, s18, 205
	s_lshr_b32 s19, s19, 11
	s_lshl_b32 s24, s18, 10
	s_add_u32 m0, s24, 0x14400
	s_mov_b32 s25, 0x8000
	s_bitcmp1_b32 s19, 1
	s_cselect_b32 s26, s16, s14
	s_cselect_b32 s27, s17, s15
	s_cselect_b32 s25, 0x200, s25
	s_add_u32 s26, s26, s25
	s_addc_u32 s27, s27, 0
	global_load_lds_dwordx4 v187, s[26:27]
	s_add_i32 s18, s12, 16
	s_mul_i32 s19, s18, 205
	s_lshr_b32 s19, s19, 11
	s_lshl_b32 s24, s18, 10
	s_add_u32 m0, s24, 0x14400
	s_mov_b32 s25, 0x8000
	s_bitcmp1_b32 s19, 1
	s_cselect_b32 s26, s16, s14
	s_cselect_b32 s27, s17, s15
	s_cselect_b32 s25, 0x200, s25
	s_add_u32 s26, s26, s25
	s_addc_u32 s27, s27, 0
	global_load_lds_dwordx4 v188, s[26:27]
	s_add_i32 s18, s12, 24
	s_mul_i32 s19, s18, 205
	s_lshr_b32 s19, s19, 11
	s_lshl_b32 s24, s18, 10
	s_add_u32 m0, s24, 0x14400
	s_mov_b32 s25, 0x8000
	s_bitcmp1_b32 s19, 1
	s_cselect_b32 s26, s16, s14
	s_cselect_b32 s27, s17, s15
	s_cselect_b32 s25, 0x200, s25
	s_add_u32 s26, s26, s25
	s_addc_u32 s27, s27, 0
	global_load_lds_dwordx4 v189, s[26:27]
	s_add_i32 s18, s12, 32
	s_mul_i32 s19, s18, 205
	s_lshr_b32 s19, s19, 11
	s_lshl_b32 s24, s18, 10
	s_add_u32 m0, s24, 0x14400
	s_mov_b32 s25, 0x8000
	s_bitcmp1_b32 s19, 1
	s_cselect_b32 s26, s16, s14
	s_cselect_b32 s27, s17, s15
	s_cselect_b32 s25, 0x200, s25
	s_add_u32 s26, s26, s25
	s_addc_u32 s27, s27, 0
	global_load_lds_dwordx4 v190, s[26:27]
	s_waitcnt vmcnt(15)
	s_branch .Lw3_dma_done
.Lw3_dma_2pairs:
	s_waitcnt vmcnt(10)
.Lw3_dma_done:
.LBB0_383:
	v_and_b32_e32 v6, 63, v6
	v_cmp_gt_u32_e32 vcc, 32, v6
	s_cmp_gt_i32 s80, 63
	s_mov_b64 s[58:59], -1
	s_waitcnt lgkmcnt(0)
	s_barrier
	s_cbranch_scc1 .LBB0_385
	v_lshlrev_b32_e32 v7, 2, v6
	v_lshlrev_b32_e32 v35, 4, v12
	v_mul_u32_u24_e32 v92, 0x90, v13
	v_xor_b32_e32 v85, 0x80, v7
	v_lshlrev_b32_e32 v84, 2, v12
	v_mad_u32_u24 v34, v13, s49, v183
	s_mov_b64 s[58:59], 0

.LBB0_387:
.LBB0_388:
	s_lshl_b32 s5, s58, 6
	s_add_i32 s10, s5, s8
	s_cmp_ge_i32 s58, s89
	s_cbranch_scc1 .LBB0_390
.LBB0_390:
	s_lshr_b32 s4, s58, 1
	s_mul_i32 s4, s4, 0xa000
	s_and_b32 s5, s58, 1
	s_mul_i32 s5, s5, 0x2800
	s_add_i32 s4, s4, s5
	s_add_i32 s11, s4, 0x400
	v_add_u32_e32 v98, s4, v96
	s_bitcmp1_b32 s58, 0
	s_cbranch_scc1 .Lw3_tile_go
	s_lshr_b32 s5, s9, 1
	s_lshr_b32 s12, s58, 1
	s_sub_i32 s5, s5, s12
	s_cmp_eq_u32 s5, 3
	s_cbranch_scc1 .Lw3_wait10
	s_cmp_eq_u32 s5, 2
	s_cbranch_scc1 .Lw3_wait5
	s_waitcnt vmcnt(0)
	s_branch .Lw3_waited
.Lw3_wait10:
	s_waitcnt vmcnt(10)
	s_branch .Lw3_waited
.Lw3_wait5:
	s_waitcnt vmcnt(5)
.Lw3_waited:
	s_barrier
.Lw3_tile_go:
.Lw3_h0:
	s_mov_b32 s101, s10
	s_sub_i32 s99, s98, s101
	s_add_i32 s100, s99, 63
	s_cmp_lt_u32 s100, 222
	s_cbranch_scc0 .Lw3_h0_end
	v_mov_b32_e32 v173, v98
	v_add_u32_e32 v172, v103, v124
	s_add_i32 s4, s11, 0x5000
	ds_read_b128 v[140:143], v173
	ds_read_b128 v[144:147], v173 offset:1280
	ds_read_b128 v[148:151], v173 offset:64
	ds_read_b128 v[152:155], v173 offset:1344
	v_mov_b32_e32 v103, s4
	s_waitcnt lgkmcnt(3)
	v_mfma_f32_16x16x32_bf16 v[34:37], v[140:143], v[50:53], v[128:131]
	v_mfma_f32_16x16x32_bf16 v[38:41], v[140:143], v[58:61], v[132:135]
	ds_read_b128 v[156:159], v172
	s_waitcnt lgkmcnt(3)
	v_mfma_f32_16x16x32_bf16 v[42:45], v[144:147], v[50:53], v[128:131]
	v_mfma_f32_16x16x32_bf16 v[46:49], v[144:147], v[58:61], v[132:135]
	ds_read_b128 v[140:143], v172 offset:2560
	s_waitcnt lgkmcnt(3)
	v_mfma_f32_16x16x32_bf16 v[34:37], v[148:151], v[54:57], v[34:37]
	v_mfma_f32_16x16x32_bf16 v[38:41], v[148:151], v[66:69], v[38:41]
	ds_read_b128 v[144:147], v172 offset:5120
	s_waitcnt lgkmcnt(3)
	v_mfma_f32_16x16x32_bf16 v[42:45], v[152:155], v[54:57], v[42:45]
	v_mfma_f32_16x16x32_bf16 v[46:49], v[152:155], v[66:69], v[46:49]
	ds_read_b128 v[148:151], v172 offset:7680
	s_waitcnt lgkmcnt(3)
	v_mfma_f32_16x16x32_bf16 v[2:5], v[156:159], v[74:77], v[2:5]
	v_mfma_f32_16x16x32_bf16 v[6:9], v[156:159], v[78:81], v[6:9]
	s_waitcnt lgkmcnt(2)
	v_mfma_f32_16x16x32_bf16 v[10:13], v[140:143], v[74:77], v[10:13]
	v_mfma_f32_16x16x32_bf16 v[14:17], v[140:143], v[78:81], v[14:17]
	s_waitcnt lgkmcnt(1)
	v_mfma_f32_16x16x32_bf16 v[18:21], v[144:147], v[74:77], v[18:21]
	v_mfma_f32_16x16x32_bf16 v[22:25], v[144:147], v[78:81], v[22:25]
	s_waitcnt lgkmcnt(0)
	v_mfma_f32_16x16x32_bf16 v[26:29], v[148:151], v[74:77], v[26:29]
	v_mfma_f32_16x16x32_bf16 v[30:33], v[148:151], v[78:81], v[30:33]
	s_cmp_lt_i32 s99, 31
	s_cbranch_scc1 .Lw3_h0_mask
	s_cmp_ge_i32 s99, 97
	s_cbranch_scc1 .Lw3_h0_wmask

.LBB0_398:
	s_cmp_eq_u32 s90, s9
	s_waitcnt lgkmcnt(0)
	s_cbranch_scc1 .LBB0_379
	s_mov_b32 s58, s90
	s_and_b32 s4, s58, 1
	s_add_i32 s90, s58, 1
	s_cmp_ge_i32 s90, s9
	s_cbranch_scc0 .LBB0_387
	s_branch .LBB0_388
